# attention v2: both items of a workgroup staged up front (one barrier), next tile's Q prefetched behind the stores, conflict-free K and bias-table layouts
# speedup vs baseline: 1.0695x; 1.0057x over previous
; #define LAS __attribute__((address_space(3)))
; __device__ __forceinline__ int otid() { int t = threadIdx.x; asm volatile("" : "+v"(t)); return t; }
; __device__ __forceinline__ int obid() { int b = blockIdx.x; asm volatile("" : "+s"(b)); return b; }
; __device__ __forceinline__ void phase_attn(const Params& p, int l, LAS unsigned char* ldsb) {
;     unsigned char* R = p.ws + WS_R;
;     const bf16_t* QKV = (const bf16_t*)(R + R_QKV); bf16_t* ATT = (bf16_t*)(R + R_ATT);
;     const float* relb = p.in[7]; const float* sinks = p.in[8] + l * 8;
;     const int tid = otid(), wid = tid >> 6, lane = tid & 63, fr = lane & 15, fq = lane >> 4;
;     LAS bf16_t* Ks = (LAS bf16_t*)ldsb;
;     LAS bf16_t* Vt = (LAS bf16_t*)(ldsb + 36864);
;     LAS float* biasL = (LAS float*)(ldsb + 70656);
;     LAS bf16_t* Pw = (LAS bf16_t*)(ldsb + 72704) + wid * (16 * 168);
;     for (int item = obid(); item < 512; item += gridDim.x) {
;         const int g = item & 1, n = (item >> 1) & 31, b = item >> 6;
;         const long tokc = (long)b * SEQ + n * 128, tokp = tokc - 128;
;         for (int idx = tid; idx < 2048; idx += 512) {
;             const int key = idx >> 3, d8 = idx & 7; u32x4 v = (u32x4){0u, 0u, 0u, 0u}, kv = (u32x4){0u, 0u, 0u, 0u};
;             if (n > 0 || key >= 128) { const bf16_t* src = QKV + (size_t)(tokp + key) * 768 + 512 + g * 64 + d8 * 8; kv = *(const u32x4*)src; v = *(const u32x4*)(src + 128); }
;             *(LAS u32x4*)(Ks + key * 72 + d8 * 8) = kv;
; #pragma unroll
;             for (int e = 0; e < 8; ++e) Vt[(d8 * 8 + e) * 264 + key] = (bf16_t)((e & 1) ? (v[e >> 1] >> 16) : (v[e >> 1] & 0xffffu));
;         }
;         { const int hl = tid >> 7, d = tid & 127; int bk = d;
;           if (d >= 16) { bk = 16 + (int)(__logf((float)d * 0.0625f) * (16.f / 2.07944154168f)); bk = bk > 31 ? 31 : bk; }
;           biasL[tid] = relb[bk * 8 + g * 4 + hl]; }
;         __syncthreads();
;         const int hl = wid >> 1, hq = g * 4 + hl; const float sink = sinks[hq];
;         for (int rt = 0; rt < 4; ++rt) {
;             const int q0 = (wid & 1) * 64 + rt * 16, kstart = q0 < 96 ? q0 : 96;
;             bf16x8 qa0, qa1; { const bf16_t* qp = QKV + (size_t)(tokc + q0 + fr) * 768 + hq * 64 + fq * 8; qa0 = *(const bf16x8*)qp; qa1 = *(const bf16x8*)(qp + 32); }
.Lat_entry:
	v_and_b32_e32 v0, 63, v183
	v_and_b32_e32 v1, 15, v183
	v_bfe_u32 v2, v183, 4, 2
	v_lshrrev_b32_e32 v4, 6, v183
	s_nop 0
	v_readfirstlane_b32 s44, v4
	s_nop 0
	s_lshr_b32 s45, s44, 1
	s_and_b32 s46, s44, 1
	v_readlane_b32 s0, v252, 0
	v_readlane_b32 s1, v252, 1
	s_sub_u32 s0, s0, 0xe0
	s_subb_u32 s1, s1, 0
	s_load_dwordx2 s[14:15], s[0:1], 0x38
	s_load_dwordx2 s[26:27], s[0:1], 0x40
	v_readlane_b32 s85, v243, 45
	s_nop 0
	s_lshr_b32 s85, s85, 1
	s_mov_b32 s82, 0x3e38aa3b
	v_lshrrev_b32_e32 v4, 3, v183
	v_and_b32_e32 v5, 7, v183
	v_mul_u32_u24_e32 v7, 1536, v4
	v_lshl_add_u32 v7, v5, 4, v7
	v_and_b32_e32 v6, 7, v4
	v_xor_b32_e32 v6, v6, v5
	v_lshlrev_b32_e32 v6, 4, v6
	v_lshl_add_u32 v6, v4, 7, v6
	v_bfe_u32 v3, v4, 1, 3
	v_xor_b32_e32 v3, v3, v5
	v_lshlrev_b32_e32 v3, 4, v3
	v_lshl_add_u32 v3, v4, 7, v3
	v_and_b32_e32 v8, 127, v183
	v_lshrrev_b32_e32 v4, 7, v183
	v_cvt_f32_u32_e32 v5, v8
	v_mul_f32_e32 v5, 0x3d800000, v5
	v_max_f32_e32 v5, 1.0, v5
	v_log_f32_e32 v5, v5
	s_nop 0
	v_mul_f32_e32 v5, 0x40aaaaab, v5
	v_cvt_i32_f32_e32 v5, v5
	v_add_u32_e32 v5, 16, v5
	v_min_u32_e32 v5, 31, v5
	v_cmp_gt_u32_e32 vcc, 16, v8
	s_nop 1
	v_cndmask_b32_e32 v10, v5, v8, vcc
	v_lshlrev_b32_e32 v10, 5, v10
	v_lshl_add_u32 v10, v4, 2, v10
	v_mul_u32_u24_e32 v9, 3328, v4
	v_sub_u32_e32 v5, 160, v8
	v_lshl_add_u32 v9, v5, 2, v9
	v_add_u32_e32 v9, 131072, v9
	v_add_u32_e32 v5, 96, v8
	v_subrev_u32_e32 v29, 32, v8
	v_cmp_gt_u32_e32 vcc, 32, v8
	s_nop 1
	v_cndmask_b32_e32 v5, v5, v29, vcc
	v_sub_u32_e32 v5, 160, v5
	v_mul_u32_u24_e32 v11, 3328, v4
	v_lshl_add_u32 v11, v5, 2, v11
	v_add_u32_e32 v11, 131072, v11
	v_lshlrev_b32_e32 v5, 2, v183
	v_add_u32_e32 v5, 144384, v5
	v_cmp_gt_u32_e32 vcc, 65, v8
	s_nop 1
	v_cndmask_b32_e32 v11, v5, v11, vcc
	v_bfe_u32 v4, v1, 1, 3
	v_xor_b32_e32 v4, v4, v2
	v_lshlrev_b32_e32 v4, 4, v4
	v_lshl_add_u32 v13, v1, 7, v4
	v_xor_b32_e32 v14, 64, v13
	v_and_b32_e32 v4, 3, v1
	v_mul_u32_u24_e32 v17, 832, v4
	v_and_b32_e32 v4, 12, v1
	v_lshlrev_b32_e32 v4, 2, v4
	v_sub_u32_e32 v17, v17, v4
	v_lshl_add_u32 v17, v2, 4, v17
	s_mul_i32 s51, s45, 3328
	s_add_u32 s51, s51, 131072
	v_add_u32_e32 v17, s51, v17
	v_lshrrev_b32_e32 v4, 2, v1
	v_lshl_add_u32 v4, v2, 2, v4
	v_and_b32_e32 v5, 7, v4
	v_bfe_u32 v29, v1, 1, 1
	v_and_b32_e32 v30, 1, v1
	v_lshlrev_b32_e32 v30, 3, v30
	v_lshl_add_u32 v30, v4, 7, v30
	v_add_u32_e32 v30, 32768, v30
	v_or_b32_e32 v4, 0, v29
	v_xor_b32_e32 v4, v4, v5
	v_lshl_add_u32 v19, v4, 4, v30
	v_or_b32_e32 v4, 2, v29
	v_xor_b32_e32 v4, v4, v5
	v_lshl_add_u32 v20, v4, 4, v30
	v_or_b32_e32 v4, 4, v29
	v_xor_b32_e32 v4, v4, v5
	v_lshl_add_u32 v21, v4, 4, v30
	v_or_b32_e32 v4, 6, v29
	v_xor_b32_e32 v4, v4, v5
	v_lshl_add_u32 v22, v4, 4, v30
	v_mul_u32_u24_e32 v27, 1536, v1
	v_lshl_add_u32 v27, v2, 4, v27
	v_lshlrev_b32_e32 v28, 10, v1
	v_lshl_add_u32 v28, v2, 3, v28
	v_xor_b32_e32 v29, 16, v0
	v_lshlrev_b32_e32 v29, 2, v29
	v_xor_b32_e32 v30, 32, v0
	v_lshlrev_b32_e32 v30, 2, v30
	s_and_b32 s2, s5, 1
	s_lshr_b32 s13, s5, 1
	s_and_b32 s13, s13, 31
	s_lshr_b32 s25, s5, 6
	s_lshl_b32 s32, s25, 12
	s_lshl_b32 s51, s13, 7
	s_add_u32 s32, s32, s51
	s_lshl_b32 s47, s2, 2
	s_add_u32 s47, s47, s45
	s_waitcnt lgkmcnt(0)
	s_lshl_b32 s51, s2, 4
	v_add_u32_e32 v4, s51, v10
	global_load_dword v34, v4, s[14:15]
	s_lshl_b32 s51, s85, 3
	s_add_u32 s51, s51, s47
	s_lshl_b32 s51, s51, 2
	s_add_u32 s36, s26, s51
	s_addc_u32 s37, s27, 0
	s_load_dword s83, s[36:37], 0x0
	s_mul_i32 s51, s32, 1536
	s_lshl_b32 s81, s2, 7
	s_add_u32 s51, s51, s81
	s_add_u32 s51, s51, 1024
	s_add_u32 s36, s74, s51
	s_addc_u32 s37, s75, 0
	s_add_u32 s38, s36, 25165824
	s_addc_u32 s39, s37, 0
	v_add_u32_e32 v15, 65536, v3
	v_add_u32_e32 v16, 65536, v6
	s_cmp_eq_u32 s13, 0
	s_nop 0
	s_cbranch_scc1 .Lat_stage_n0
	s_sub_u32 s36, s36, 196608
	s_subb_u32 s37, s37, 0
	s_sub_u32 s38, s38, 196608
	s_subb_u32 s39, s39, 0
	global_load_dwordx4 v[60:63], v7, s[36:37]
	global_load_dwordx4 v[64:67], v7, s[36:37] offset:256
	s_add_u32 s36, s36, 98304
	s_addc_u32 s37, s37, 0
	global_load_dwordx4 v[68:71], v7, s[38:39]
	global_load_dwordx4 v[72:75], v7, s[38:39] offset:256
	s_add_u32 s38, s38, 98304
	s_addc_u32 s39, s39, 0
	global_load_dwordx4 v[76:79], v7, s[36:37]
	global_load_dwordx4 v[80:83], v7, s[36:37] offset:256
	s_add_u32 s36, s36, 98304
	s_addc_u32 s37, s37, 0
	global_load_dwordx4 v[84:87], v7, s[38:39]
	global_load_dwordx4 v[88:91], v7, s[38:39] offset:256
	s_add_u32 s38, s38, 98304
	s_addc_u32 s39, s39, 0
	global_load_dwordx4 v[92:95], v7, s[36:37]
	global_load_dwordx4 v[96:99], v7, s[36:37] offset:256
	s_add_u32 s36, s36, 98304
	s_addc_u32 s37, s37, 0
	global_load_dwordx4 v[100:103], v7, s[38:39]
	global_load_dwordx4 v[104:107], v7, s[38:39] offset:256
	s_add_u32 s38, s38, 98304
	s_addc_u32 s39, s39, 0
	global_load_dwordx4 v[108:111], v7, s[36:37]
	global_load_dwordx4 v[112:115], v7, s[36:37] offset:256
	global_load_dwordx4 v[116:119], v7, s[38:39]
	global_load_dwordx4 v[120:123], v7, s[38:39] offset:256
	s_mov_b32 s51, 0
	s_lshr_b32 s81, s51, 2
	s_lshl_b32 s81, s81, 14
	s_and_b32 s51, s51, 3
	s_lshl_b32 s51, s51, 4
	s_add_u32 s81, s81, s51
	s_lshl_b32 s51, s46, 6
	s_add_u32 s81, s81, s51
	s_add_u32 s81, s81, s32
	s_mul_i32 s81, s81, 1536
	s_lshl_b32 s51, s47, 7
	s_add_u32 s81, s81, s51
	s_add_u32 s40, s74, s81
	s_addc_u32 s41, s75, 0
	global_load_dwordx4 v[36:39], v27, s[40:41]
	global_load_dwordx4 v[40:43], v27, s[40:41] offset:64
	s_waitcnt vmcnt(18)
	v_mul_f32_e32 v34, 0x3fb8aa3b, v34
	v_mov_b32_e32 v35, 0xff800000
	ds_write_b32 v9, v34 offset:0
	ds_write_b32 v11, v35 offset:0
	ds_write_b32 v9, v34 offset:836
	ds_write_b32 v11, v35 offset:836
	ds_write_b32 v9, v34 offset:1672
	ds_write_b32 v11, v35 offset:1672
	ds_write_b32 v9, v34 offset:2508
	ds_write_b32 v11, v35 offset:2508
	s_waitcnt vmcnt(16)
	ds_write_b128 v3, v[60:63] offset:0
	ds_write_b128 v6, v[64:67] offset:32768
	s_waitcnt vmcnt(14)
	ds_write_b128 v15, v[68:71] offset:0
	ds_write_b128 v16, v[72:75] offset:32768
	s_waitcnt vmcnt(12)
	ds_write_b128 v3, v[76:79] offset:8192
	ds_write_b128 v6, v[80:83] offset:40960
	s_waitcnt vmcnt(10)
	ds_write_b128 v15, v[84:87] offset:8192
	ds_write_b128 v16, v[88:91] offset:40960
	s_waitcnt vmcnt(8)
	ds_write_b128 v3, v[92:95] offset:16384
	ds_write_b128 v6, v[96:99] offset:49152
	s_waitcnt vmcnt(6)
	ds_write_b128 v15, v[100:103] offset:16384
	ds_write_b128 v16, v[104:107] offset:49152
	s_waitcnt vmcnt(4)
	ds_write_b128 v3, v[108:111] offset:24576
	ds_write_b128 v6, v[112:115] offset:57344
	s_waitcnt vmcnt(2)
	ds_write_b128 v15, v[116:119] offset:24576
	ds_write_b128 v16, v[120:123] offset:57344
	s_branch .Lat_staged
; #define LAS __attribute__((address_space(3)))
; __device__ __forceinline__ void phase_attn(const Params& p, int l, LAS unsigned char* ldsb) {
;     ...
;         for (int idx = tid; idx < 2048; idx += 512) {
;             const int key = idx >> 3, d8 = idx & 7; u32x4 v = (u32x4){0u, 0u, 0u, 0u}, kv = (u32x4){0u, 0u, 0u, 0u};
;             if (n > 0 || key >= 128) { const bf16_t* src = QKV + (size_t)(tokp + key) * 768 + 512 + g * 64 + d8 * 8; kv = *(const u32x4*)src; v = *(const u32x4*)(src + 128); }
;             *(LAS u32x4*)(Ks + key * 72 + d8 * 8) = kv;
; #pragma unroll
;             for (int e = 0; e < 8; ++e) Vt[(d8 * 8 + e) * 264 + key] = (bf16_t)((e & 1) ? (v[e >> 1] >> 16) : (v[e >> 1] & 0xffffu));
;         }
;         { const int hl = tid >> 7, d = tid & 127; int bk = d;
;           if (d >= 16) { bk = 16 + (int)(__logf((float)d * 0.0625f) * (16.f / 2.07944154168f)); bk = bk > 31 ? 31 : bk; }
;           biasL[tid] = relb[bk * 8 + g * 4 + hl]; }
;         __syncthreads();
;         const int hl = wid >> 1, hq = g * 4 + hl; const float sink = sinks[hq];
;         for (int rt = 0; rt < 4; ++rt) {
;             const int q0 = (wid & 1) * 64 + rt * 16, kstart = q0 < 96 ? q0 : 96;
;             bf16x8 qa0, qa1; { const bf16_t* qp = QKV + (size_t)(tokc + q0 + fr) * 768 + hq * 64 + fq * 8; qa0 = *(const bf16x8*)qp; qa1 = *(const bf16x8*)(qp + 32); }
;             f32x4 S[10];
; #pragma unroll
;             for (int kt = 0; kt < 10; ++kt) {
;                 LAS const bf16_t* kp = Ks + (kstart + kt * 16 + fr) * 72 + fq * 8;
;                 const bf16x8 k0 = *(LAS const bf16x8*)kp, k1 = *(LAS const bf16x8*)(kp + 32);
;                 f32x4 z = (f32x4){0.f, 0.f, 0.f, 0.f};
;                 z = __builtin_amdgcn_mfma_f32_16x16x32_bf16(qa0, k0, z, 0, 0, 0);
;                 z = __builtin_amdgcn_mfma_f32_16x16x32_bf16(qa1, k1, z, 0, 0, 0);
;                 S[kt] = z;
;             }
.Lat_stage_n0:
	global_load_dwordx4 v[92:95], v7, s[36:37]
	global_load_dwordx4 v[96:99], v7, s[36:37] offset:256
	s_add_u32 s36, s36, 98304
	s_addc_u32 s37, s37, 0
	global_load_dwordx4 v[100:103], v7, s[38:39]
	global_load_dwordx4 v[104:107], v7, s[38:39] offset:256
	s_add_u32 s38, s38, 98304
	s_addc_u32 s39, s39, 0
	global_load_dwordx4 v[108:111], v7, s[36:37]
	global_load_dwordx4 v[112:115], v7, s[36:37] offset:256
	global_load_dwordx4 v[116:119], v7, s[38:39]
	global_load_dwordx4 v[120:123], v7, s[38:39] offset:256
	s_mov_b32 s51, 0
	s_lshr_b32 s81, s51, 2
	s_lshl_b32 s81, s81, 14
	s_and_b32 s51, s51, 3
	s_lshl_b32 s51, s51, 4
	s_add_u32 s81, s81, s51
	s_lshl_b32 s51, s46, 6
	s_add_u32 s81, s81, s51
	s_add_u32 s81, s81, s32
	s_mul_i32 s81, s81, 1536
	s_lshl_b32 s51, s47, 7
	s_add_u32 s81, s81, s51
	s_add_u32 s40, s74, s81
	s_addc_u32 s41, s75, 0
	global_load_dwordx4 v[36:39], v27, s[40:41]
	global_load_dwordx4 v[40:43], v27, s[40:41] offset:64
	v_mov_b32_e32 v60, 0
	v_mov_b32_e32 v61, 0
	v_mov_b32_e32 v62, 0
	v_mov_b32_e32 v63, 0
	ds_write_b128 v3, v[60:63] offset:0
	ds_write_b128 v6, v[60:63] offset:32768
	ds_write_b128 v15, v[60:63] offset:0
	ds_write_b128 v16, v[60:63] offset:32768
	ds_write_b128 v3, v[60:63] offset:8192
	ds_write_b128 v6, v[60:63] offset:40960
	ds_write_b128 v15, v[60:63] offset:8192
	ds_write_b128 v16, v[60:63] offset:40960
	s_waitcnt vmcnt(10)
	v_mul_f32_e32 v34, 0x3fb8aa3b, v34
	v_mov_b32_e32 v35, 0xff800000
	ds_write_b32 v9, v34 offset:0
	ds_write_b32 v11, v35 offset:0
	ds_write_b32 v9, v34 offset:836
	ds_write_b32 v11, v35 offset:836
	ds_write_b32 v9, v34 offset:1672
	ds_write_b32 v11, v35 offset:1672
	ds_write_b32 v9, v34 offset:2508
	ds_write_b32 v11, v35 offset:2508
	s_waitcnt vmcnt(8)
	ds_write_b128 v3, v[92:95] offset:16384
	ds_write_b128 v6, v[96:99] offset:49152
	s_waitcnt vmcnt(6)
	ds_write_b128 v15, v[100:103] offset:16384
	ds_write_b128 v16, v[104:107] offset:49152
	s_waitcnt vmcnt(4)
	ds_write_b128 v3, v[108:111] offset:24576
	ds_write_b128 v6, v[112:115] offset:57344
	s_waitcnt vmcnt(2)
	ds_write_b128 v15, v[116:119] offset:24576
	ds_write_b128 v16, v[120:123] offset:57344
.Lat_staged:
	s_waitcnt vmcnt(0) lgkmcnt(0)
	s_barrier
	v_mov_b32_e32 v4, s83
	v_mul_f32_e32 v4, 0x3fb8aa3b, v4
	s_nop 0
	v_readfirstlane_b32 s83, v4
	s_mov_b32 s48, 0
	s_nop 3
.Lat_rt:
	s_and_b32 s51, s48, 3
	s_lshl_b32 s51, s51, 4
	s_lshl_b32 s49, s46, 6
	s_add_u32 s49, s49, s51
	s_min_u32 s50, s49, 96
	s_lshr_b32 s51, s48, 2
	s_lshl_b32 s81, s51, 14
	s_add_u32 s81, s81, s32
	s_add_u32 s81, s81, s49
	s_lshl_b32 s81, s81, 10
	s_lshl_b32 s84, s47, 7
	s_add_u32 s81, s81, s84
	s_add_u32 s81, s81, 0x7000000
	s_add_u32 s42, s74, s81
	s_addc_u32 s43, s75, 0
	s_lshl_b32 s51, s51, 16
	s_lshl_b32 s81, s50, 7
	s_add_u32 s51, s51, s81
	v_add_u32_e32 v15, s51, v13
	v_add_u32_e32 v16, s51, v14
	v_add_u32_e32 v23, s51, v19
	v_add_u32_e32 v24, s51, v20
	v_add_u32_e32 v25, s51, v21
	v_add_u32_e32 v26, s51, v22
	s_sub_u32 s81, s49, s50
	s_sub_u32 s81, 32, s81
	s_lshl_b32 s81, s81, 2
	v_add_u32_e32 v18, s81, v17
	s_sub_u32 s84, 128, s50
	s_lshr_b32 s84, s84, 4
	s_cmp_eq_u32 s13, 0
	s_cselect_b32 s84, s84, 0
	ds_read_b128 v[100:103], v18 offset:0
	ds_read_b128 v[104:107], v18 offset:64
	ds_read_b128 v[108:111], v18 offset:128
	ds_read_b128 v[112:115], v18 offset:192
	ds_read_b128 v[116:119], v18 offset:256
	ds_read_b128 v[120:123], v18 offset:320
	ds_read_b128 v[124:127], v18 offset:384
	ds_read_b128 v[128:131], v18 offset:448
	ds_read_b128 v[132:135], v18 offset:512
	ds_read_b128 v[136:139], v18 offset:576
	ds_read_b128 v[44:47], v15 offset:0
	ds_read_b128 v[48:51], v16 offset:0
	ds_read_b128 v[52:55], v15 offset:2048
	ds_read_b128 v[56:59], v16 offset:2048
	s_waitcnt lgkmcnt(2)
	v_mfma_f32_16x16x32_bf16 v[60:63], v[44:47], v[36:39], 0
	v_mfma_f32_16x16x32_bf16 v[60:63], v[48:51], v[40:43], v[60:63]
	ds_read_b128 v[44:47], v15 offset:4096
	ds_read_b128 v[48:51], v16 offset:4096
	s_waitcnt lgkmcnt(2)
	v_mfma_f32_16x16x32_bf16 v[64:67], v[52:55], v[36:39], 0
	v_mfma_f32_16x16x32_bf16 v[64:67], v[56:59], v[40:43], v[64:67]
	ds_read_b128 v[52:55], v15 offset:6144
	ds_read_b128 v[56:59], v16 offset:6144
	s_waitcnt lgkmcnt(2)
	v_mfma_f32_16x16x32_bf16 v[68:71], v[44:47], v[36:39], 0
	v_mfma_f32_16x16x32_bf16 v[68:71], v[48:51], v[40:43], v[68:71]
	ds_read_b128 v[44:47], v15 offset:8192
	ds_read_b128 v[48:51], v16 offset:8192
	s_waitcnt lgkmcnt(2)
	v_mfma_f32_16x16x32_bf16 v[72:75], v[52:55], v[36:39], 0
	v_mfma_f32_16x16x32_bf16 v[72:75], v[56:59], v[40:43], v[72:75]
	ds_read_b128 v[52:55], v15 offset:10240
	ds_read_b128 v[56:59], v16 offset:10240
	s_waitcnt lgkmcnt(2)
	v_mfma_f32_16x16x32_bf16 v[76:79], v[44:47], v[36:39], 0
	v_mfma_f32_16x16x32_bf16 v[76:79], v[48:51], v[40:43], v[76:79]
	ds_read_b128 v[44:47], v15 offset:12288
	ds_read_b128 v[48:51], v16 offset:12288
	s_waitcnt lgkmcnt(2)
	v_mfma_f32_16x16x32_bf16 v[80:83], v[52:55], v[36:39], 0
	v_mfma_f32_16x16x32_bf16 v[80:83], v[56:59], v[40:43], v[80:83]
	ds_read_b128 v[52:55], v15 offset:14336
	ds_read_b128 v[56:59], v16 offset:14336
	s_waitcnt lgkmcnt(2)
	v_mfma_f32_16x16x32_bf16 v[84:87], v[44:47], v[36:39], 0
	v_mfma_f32_16x16x32_bf16 v[84:87], v[48:51], v[40:43], v[84:87]
	ds_read_b128 v[44:47], v15 offset:16384
	ds_read_b128 v[48:51], v16 offset:16384
	s_waitcnt lgkmcnt(2)
	v_mfma_f32_16x16x32_bf16 v[88:91], v[52:55], v[36:39], 0
	v_mfma_f32_16x16x32_bf16 v[88:91], v[56:59], v[40:43], v[88:91]
	ds_read_b128 v[52:55], v15 offset:18432
	ds_read_b128 v[56:59], v16 offset:18432
	s_waitcnt lgkmcnt(2)
	v_mfma_f32_16x16x32_bf16 v[92:95], v[44:47], v[36:39], 0
	v_mfma_f32_16x16x32_bf16 v[92:95], v[48:51], v[40:43], v[92:95]
	s_waitcnt lgkmcnt(0)
; #define LAS __attribute__((address_space(3)))
; __device__ __forceinline__ void phase_attn(const Params& p, int l, LAS unsigned char* ldsb) {
;     ...
;             for (int kt = 0; kt < 10; ++kt) {
;                 LAS const bf16_t* kp = Ks + (kstart + kt * 16 + fr) * 72 + fq * 8;
;                 const bf16x8 k0 = *(LAS const bf16x8*)kp, k1 = *(LAS const bf16x8*)(kp + 32);
;                 f32x4 z = (f32x4){0.f, 0.f, 0.f, 0.f};
;                 z = __builtin_amdgcn_mfma_f32_16x16x32_bf16(qa0, k0, z, 0, 0, 0);
;                 z = __builtin_amdgcn_mfma_f32_16x16x32_bf16(qa1, k1, z, 0, 0, 0);
;                 S[kt] = z;
;             }
;             float mx[4] = {-INFINITY, -INFINITY, -INFINITY, -INFINITY};
; #pragma unroll
;             for (int kt = 0; kt < 10; ++kt)
; #pragma unroll
;                 for (int j = 0; j < 4; ++j) {
;                     const int key = kstart + kt * 16 + fr, dist = q0 + 4 * fq + j + 128 - key;
;                     const bool ok = (dist >= 0) && (dist < 128) && (n > 0 || key >= 128);
;                     const float s = ok ? (S[kt][j] * 0.125f + biasL[hl * 128 + (dist & 127)]) : -INFINITY;
;                     S[kt][j] = s; mx[j] = fmaxf(mx[j], s);
;                 }
;             float inv[4];
; #pragma unroll
;             for (int j = 0; j < 4; ++j) mx[j] = fmaxf(row16_max(mx[j]), sink);
;             float sm[4] = {0.f, 0.f, 0.f, 0.f};
; #pragma unroll
;             for (int kt = 0; kt < 10; ++kt)
; #pragma unroll
;                 for (int j = 0; j < 4; ++j) { const float e = __expf(S[kt][j] - mx[j]); S[kt][j] = e; sm[j] += e; }
	v_mfma_f32_16x16x32_bf16 v[96:99], v[52:55], v[36:39], 0
	v_mfma_f32_16x16x32_bf16 v[96:99], v[56:59], v[40:43], v[96:99]
	s_add_u32 s51, s48, 1
	s_min_u32 s51, s51, 7
	s_lshr_b32 s81, s51, 2
	s_lshl_b32 s81, s81, 14
	s_and_b32 s51, s51, 3
	s_lshl_b32 s51, s51, 4
	s_add_u32 s81, s81, s51
	s_lshl_b32 s51, s46, 6
	s_add_u32 s81, s81, s51
	s_add_u32 s81, s81, s32
	s_mul_i32 s81, s81, 1536
	s_lshl_b32 s51, s47, 7
	s_add_u32 s81, s81, s51
	s_add_u32 s40, s74, s81
	s_addc_u32 s41, s75, 0
	global_load_dwordx4 v[36:39], v27, s[40:41]
	global_load_dwordx4 v[40:43], v27, s[40:41] offset:64
	v_fma_f32 v60, v60, s82, v100
	v_fma_f32 v61, v61, s82, v101
	v_fma_f32 v62, v62, s82, v102
	v_fma_f32 v63, v63, s82, v103
	v_fma_f32 v64, v64, s82, v104
	v_fma_f32 v65, v65, s82, v105
	v_fma_f32 v66, v66, s82, v106
	v_fma_f32 v67, v67, s82, v107
	v_fma_f32 v68, v68, s82, v108
	v_fma_f32 v69, v69, s82, v109
	v_fma_f32 v70, v70, s82, v110
	v_fma_f32 v71, v71, s82, v111
	v_fma_f32 v72, v72, s82, v112
	v_fma_f32 v73, v73, s82, v113
	v_fma_f32 v74, v74, s82, v114
	v_fma_f32 v75, v75, s82, v115
	v_fma_f32 v76, v76, s82, v116
	v_fma_f32 v77, v77, s82, v117
	v_fma_f32 v78, v78, s82, v118
	v_fma_f32 v79, v79, s82, v119
	v_fma_f32 v80, v80, s82, v120
	v_fma_f32 v81, v81, s82, v121
	v_fma_f32 v82, v82, s82, v122
	v_fma_f32 v83, v83, s82, v123
	v_fma_f32 v84, v84, s82, v124
	v_fma_f32 v85, v85, s82, v125
	v_fma_f32 v86, v86, s82, v126
	v_fma_f32 v87, v87, s82, v127
	v_fma_f32 v88, v88, s82, v128
	v_fma_f32 v89, v89, s82, v129
	v_fma_f32 v90, v90, s82, v130
	v_fma_f32 v91, v91, s82, v131
	v_fma_f32 v92, v92, s82, v132
	v_fma_f32 v93, v93, s82, v133
	v_fma_f32 v94, v94, s82, v134
	v_fma_f32 v95, v95, s82, v135
	v_fma_f32 v96, v96, s82, v136
	v_fma_f32 v97, v97, s82, v137
	v_fma_f32 v98, v98, s82, v138
	v_fma_f32 v99, v99, s82, v139
	s_cmp_eq_u32 s84, 0
	s_nop 0
	s_cbranch_scc1 .Lat_nomask
	s_cmp_gt_u32 s84, 0
	s_cselect_b32 s86, 0xff800000, 0
	v_add_f32_e32 v60, s86, v60
	v_add_f32_e32 v61, s86, v61
	v_add_f32_e32 v62, s86, v62
	v_add_f32_e32 v63, s86, v63
	s_cmp_gt_u32 s84, 1
	s_cselect_b32 s86, 0xff800000, 0
	v_add_f32_e32 v64, s86, v64
	v_add_f32_e32 v65, s86, v65
	v_add_f32_e32 v66, s86, v66
	v_add_f32_e32 v67, s86, v67
	s_cmp_gt_u32 s84, 2
	s_cselect_b32 s86, 0xff800000, 0
	v_add_f32_e32 v68, s86, v68
	v_add_f32_e32 v69, s86, v69
	v_add_f32_e32 v70, s86, v70
	v_add_f32_e32 v71, s86, v71
	s_cmp_gt_u32 s84, 3
	s_cselect_b32 s86, 0xff800000, 0
	v_add_f32_e32 v72, s86, v72
	v_add_f32_e32 v73, s86, v73
	v_add_f32_e32 v74, s86, v74
	v_add_f32_e32 v75, s86, v75
	s_cmp_gt_u32 s84, 4
	s_cselect_b32 s86, 0xff800000, 0
	v_add_f32_e32 v76, s86, v76
	v_add_f32_e32 v77, s86, v77
	v_add_f32_e32 v78, s86, v78
	v_add_f32_e32 v79, s86, v79
	s_cmp_gt_u32 s84, 5
	s_cselect_b32 s86, 0xff800000, 0
	v_add_f32_e32 v80, s86, v80
	v_add_f32_e32 v81, s86, v81
	v_add_f32_e32 v82, s86, v82
	v_add_f32_e32 v83, s86, v83
	s_cmp_gt_u32 s84, 6
	s_cselect_b32 s86, 0xff800000, 0
	v_add_f32_e32 v84, s86, v84
	v_add_f32_e32 v85, s86, v85
	v_add_f32_e32 v86, s86, v86
	v_add_f32_e32 v87, s86, v87
	s_cmp_gt_u32 s84, 7
	s_cselect_b32 s86, 0xff800000, 0
	v_add_f32_e32 v88, s86, v88
	v_add_f32_e32 v89, s86, v89
	v_add_f32_e32 v90, s86, v90
	v_add_f32_e32 v91, s86, v91
	s_nop 1
.Lat_nomask:
	v_max3_f32 v31, v60, v61, v62
	v_max3_f32 v31, v31, v63, v64
	v_max3_f32 v31, v31, v65, v66
	v_max3_f32 v31, v31, v67, v68
	v_max3_f32 v31, v31, v69, v70
	v_max3_f32 v31, v31, v71, v72
	v_max3_f32 v31, v31, v73, v74
	v_max3_f32 v31, v31, v75, v76
	v_max3_f32 v31, v31, v77, v78
	v_max3_f32 v31, v31, v79, v80
	v_max3_f32 v31, v31, v81, v82
	v_max3_f32 v31, v31, v83, v84
	v_max3_f32 v31, v31, v85, v86
	v_max3_f32 v31, v31, v87, v88
	v_max3_f32 v31, v31, v89, v90
	v_max3_f32 v31, v31, v91, v92
	v_max3_f32 v31, v31, v93, v94
	v_max3_f32 v31, v31, v95, v96
	v_max3_f32 v31, v31, v97, v98
	v_max_f32_e32 v31, v31, v99
	ds_bpermute_b32 v34, v29, v31
	s_waitcnt lgkmcnt(0)
	v_max_f32_e32 v31, v31, v34
	ds_bpermute_b32 v34, v30, v31
	s_waitcnt lgkmcnt(0)
	v_max_f32_e32 v31, v31, v34
	v_max_f32_e32 v31, s83, v31
	v_sub_f32_e32 v60, v60, v31
	v_sub_f32_e32 v61, v61, v31
	v_sub_f32_e32 v62, v62, v31
	v_sub_f32_e32 v63, v63, v31
	v_sub_f32_e32 v64, v64, v31
	v_sub_f32_e32 v65, v65, v31
	v_sub_f32_e32 v66, v66, v31
	v_sub_f32_e32 v67, v67, v31
	v_sub_f32_e32 v68, v68, v31
	v_sub_f32_e32 v69, v69, v31
	v_sub_f32_e32 v70, v70, v31
	v_sub_f32_e32 v71, v71, v31
	v_sub_f32_e32 v72, v72, v31
	v_sub_f32_e32 v73, v73, v31
	v_sub_f32_e32 v74, v74, v31
	v_sub_f32_e32 v75, v75, v31
	v_sub_f32_e32 v76, v76, v31
	v_sub_f32_e32 v77, v77, v31
	v_sub_f32_e32 v78, v78, v31
	v_sub_f32_e32 v79, v79, v31
	v_sub_f32_e32 v80, v80, v31
	v_sub_f32_e32 v81, v81, v31
	v_sub_f32_e32 v82, v82, v31
	v_sub_f32_e32 v83, v83, v31
	v_sub_f32_e32 v84, v84, v31
	v_sub_f32_e32 v85, v85, v31
	v_sub_f32_e32 v86, v86, v31
	v_sub_f32_e32 v87, v87, v31
	v_sub_f32_e32 v88, v88, v31
	v_sub_f32_e32 v89, v89, v31
	v_sub_f32_e32 v90, v90, v31
	v_sub_f32_e32 v91, v91, v31
	v_sub_f32_e32 v92, v92, v31
	v_sub_f32_e32 v93, v93, v31
	v_sub_f32_e32 v94, v94, v31
	v_sub_f32_e32 v95, v95, v31
	v_sub_f32_e32 v96, v96, v31
	v_sub_f32_e32 v97, v97, v31
	v_sub_f32_e32 v98, v98, v31
	v_sub_f32_e32 v99, v99, v31
	v_exp_f32_e32 v60, v60
	v_exp_f32_e32 v61, v61
	v_exp_f32_e32 v62, v62
	v_exp_f32_e32 v63, v63
	v_exp_f32_e32 v64, v64
	v_exp_f32_e32 v65, v65
	v_exp_f32_e32 v66, v66
	v_exp_f32_e32 v67, v67
	v_exp_f32_e32 v68, v68
	v_exp_f32_e32 v69, v69
	v_exp_f32_e32 v70, v70
	v_exp_f32_e32 v71, v71
	v_exp_f32_e32 v72, v72
	v_exp_f32_e32 v73, v73
	v_exp_f32_e32 v74, v74
	v_exp_f32_e32 v75, v75
; #define LAS __attribute__((address_space(3)))
; __device__ __forceinline__ unsigned pk_bf16(float lo, float hi) { const f32x2_t f = {lo, hi}; return __builtin_bit_cast(unsigned, __builtin_convertvector(f, bf16x2_t)); }
; __device__ __forceinline__ void phase_attn(const Params& p, int l, LAS unsigned char* ldsb) {
;     ...
;             float sm[4] = {0.f, 0.f, 0.f, 0.f};
; #pragma unroll
;             for (int kt = 0; kt < 10; ++kt)
; #pragma unroll
;                 for (int j = 0; j < 4; ++j) { const float e = __expf(S[kt][j] - mx[j]); S[kt][j] = e; sm[j] += e; }
; #pragma unroll
;             for (int j = 0; j < 4; ++j) inv[j] = 1.f / (row16_sum(sm[j]) + __expf(sink - mx[j]));
; #pragma unroll
;             for (int kt = 0; kt < 10; ++kt)
; #pragma unroll
;                 for (int j = 0; j < 4; ++j) Pw[(4 * fq + j) * 168 + kt * 16 + fr] = (bf16_t)(pk_bf16(S[kt][j] * inv[j], 0.f) & 0xffffu);
;             asm volatile("s_waitcnt lgkmcnt(0)" ::: "memory");
;             __builtin_amdgcn_wave_barrier();
;             f32x4 O[4];
; #pragma unroll
;             for (int dt = 0; dt < 4; ++dt) O[dt] = (f32x4){0.f, 0.f, 0.f, 0.f};
; #pragma unroll
;             for (int kk = 0; kk < 5; ++kk) {
;                 const bf16x8 pa = *(LAS const bf16x8*)(Pw + fr * 168 + kk * 32 + fq * 8);
; #pragma unroll
;                 for (int dt = 0; dt < 4; ++dt) {
;                     const bf16x8 vb = *(LAS const bf16x8*)(Vt + (dt * 16 + fr) * 264 + kstart + kk * 32 + fq * 8);
;                     O[dt] = __builtin_amdgcn_mfma_f32_16x16x32_bf16(pa, vb, O[dt], 0, 0, 0);
	v_exp_f32_e32 v76, v76
	v_exp_f32_e32 v77, v77
	v_exp_f32_e32 v78, v78
	v_exp_f32_e32 v79, v79
	v_exp_f32_e32 v80, v80
	v_exp_f32_e32 v81, v81
	v_exp_f32_e32 v82, v82
	v_exp_f32_e32 v83, v83
	v_exp_f32_e32 v84, v84
	v_exp_f32_e32 v85, v85
	v_exp_f32_e32 v86, v86
	v_exp_f32_e32 v87, v87
	v_exp_f32_e32 v88, v88
	v_exp_f32_e32 v89, v89
	v_exp_f32_e32 v90, v90
	v_exp_f32_e32 v91, v91
	v_exp_f32_e32 v92, v92
	v_exp_f32_e32 v93, v93
	v_exp_f32_e32 v94, v94
	v_exp_f32_e32 v95, v95
	v_exp_f32_e32 v96, v96
	v_exp_f32_e32 v97, v97
	v_exp_f32_e32 v98, v98
	v_exp_f32_e32 v99, v99
	v_add_f32_e32 v32, v60, v61
	v_add_f32_e32 v32, v32, v62
	v_add_f32_e32 v32, v32, v63
	v_add_f32_e32 v32, v32, v64
	v_add_f32_e32 v32, v32, v65
	v_add_f32_e32 v32, v32, v66
	v_add_f32_e32 v32, v32, v67
	v_add_f32_e32 v32, v32, v68
	v_add_f32_e32 v32, v32, v69
	v_add_f32_e32 v32, v32, v70
	v_add_f32_e32 v32, v32, v71
	v_add_f32_e32 v32, v32, v72
	v_add_f32_e32 v32, v32, v73
	v_add_f32_e32 v32, v32, v74
	v_add_f32_e32 v32, v32, v75
	v_add_f32_e32 v32, v32, v76
	v_add_f32_e32 v32, v32, v77
	v_add_f32_e32 v32, v32, v78
	v_add_f32_e32 v32, v32, v79
	v_add_f32_e32 v32, v32, v80
	v_add_f32_e32 v32, v32, v81
	v_add_f32_e32 v32, v32, v82
	v_add_f32_e32 v32, v32, v83
	v_add_f32_e32 v32, v32, v84
	v_add_f32_e32 v32, v32, v85
	v_add_f32_e32 v32, v32, v86
	v_add_f32_e32 v32, v32, v87
	v_add_f32_e32 v32, v32, v88
	v_add_f32_e32 v32, v32, v89
	v_add_f32_e32 v32, v32, v90
	v_add_f32_e32 v32, v32, v91
	v_add_f32_e32 v32, v32, v92
	v_add_f32_e32 v32, v32, v93
	v_add_f32_e32 v32, v32, v94
	v_add_f32_e32 v32, v32, v95
	v_add_f32_e32 v32, v32, v96
	v_add_f32_e32 v32, v32, v97
	v_add_f32_e32 v32, v32, v98
	v_add_f32_e32 v32, v32, v99
	ds_bpermute_b32 v34, v29, v32
	s_waitcnt lgkmcnt(0)
	v_add_f32_e32 v32, v32, v34
	ds_bpermute_b32 v34, v30, v32
	s_waitcnt lgkmcnt(0)
	v_add_f32_e32 v32, v32, v34
	v_sub_f32_e32 v34, s83, v31
	v_exp_f32_e32 v34, v34
	s_nop 0
	v_add_f32_e32 v32, v32, v34
	v_rcp_f32_e32 v33, v32
	s_nop 0
	v_fma_f32 v34, -v32, v33, 2.0
	v_mul_f32_e32 v33, v33, v34
	v_mul_f32_e32 v60, v33, v60
	v_mul_f32_e32 v61, v33, v61
	v_cvt_pk_bf16_f32 v140, v60, v61
	v_mul_f32_e32 v62, v33, v62
	v_mul_f32_e32 v63, v33, v63
	v_cvt_pk_bf16_f32 v141, v62, v63
	v_mul_f32_e32 v64, v33, v64
	v_mul_f32_e32 v65, v33, v65
	v_cvt_pk_bf16_f32 v142, v64, v65
	v_mul_f32_e32 v66, v33, v66
	v_mul_f32_e32 v67, v33, v67
	v_cvt_pk_bf16_f32 v143, v66, v67
	v_mul_f32_e32 v68, v33, v68
	v_mul_f32_e32 v69, v33, v69
	v_cvt_pk_bf16_f32 v144, v68, v69
	v_mul_f32_e32 v70, v33, v70
	v_mul_f32_e32 v71, v33, v71
	v_cvt_pk_bf16_f32 v145, v70, v71
	v_mul_f32_e32 v72, v33, v72
	v_mul_f32_e32 v73, v33, v73
	v_cvt_pk_bf16_f32 v146, v72, v73
	v_mul_f32_e32 v74, v33, v74
	v_mul_f32_e32 v75, v33, v75
	v_cvt_pk_bf16_f32 v147, v74, v75
	v_mul_f32_e32 v76, v33, v76
	v_mul_f32_e32 v77, v33, v77
	v_cvt_pk_bf16_f32 v148, v76, v77
	v_mul_f32_e32 v78, v33, v78
	v_mul_f32_e32 v79, v33, v79
	v_cvt_pk_bf16_f32 v149, v78, v79
	v_mul_f32_e32 v80, v33, v80
	v_mul_f32_e32 v81, v33, v81
	v_cvt_pk_bf16_f32 v150, v80, v81
	v_mul_f32_e32 v82, v33, v82
	v_mul_f32_e32 v83, v33, v83
	v_cvt_pk_bf16_f32 v151, v82, v83
	v_mul_f32_e32 v84, v33, v84
	v_mul_f32_e32 v85, v33, v85
	v_cvt_pk_bf16_f32 v152, v84, v85
	v_mul_f32_e32 v86, v33, v86
	v_mul_f32_e32 v87, v33, v87
	v_cvt_pk_bf16_f32 v153, v86, v87
	v_mul_f32_e32 v88, v33, v88
	v_mul_f32_e32 v89, v33, v89
	v_cvt_pk_bf16_f32 v154, v88, v89
	v_mul_f32_e32 v90, v33, v90
	v_mul_f32_e32 v91, v33, v91
	v_cvt_pk_bf16_f32 v155, v90, v91
	v_mul_f32_e32 v92, v33, v92
	v_mul_f32_e32 v93, v33, v93
	v_cvt_pk_bf16_f32 v156, v92, v93
	v_mul_f32_e32 v94, v33, v94
	v_mul_f32_e32 v95, v33, v95
	v_cvt_pk_bf16_f32 v157, v94, v95
	v_mul_f32_e32 v96, v33, v96
	v_mul_f32_e32 v97, v33, v97
	v_cvt_pk_bf16_f32 v158, v96, v97
	v_mul_f32_e32 v98, v33, v98
	v_mul_f32_e32 v99, v33, v99
	v_cvt_pk_bf16_f32 v159, v98, v99
	ds_read_b64_tr_b16 v[196:197], v23 offset:0
	ds_read_b64_tr_b16 v[198:199], v23 offset:2048
	ds_read_b64_tr_b16 v[200:201], v24 offset:0
	ds_read_b64_tr_b16 v[202:203], v24 offset:2048
	ds_read_b64_tr_b16 v[204:205], v25 offset:0
	ds_read_b64_tr_b16 v[206:207], v25 offset:2048
	ds_read_b64_tr_b16 v[208:209], v26 offset:0
	ds_read_b64_tr_b16 v[210:211], v26 offset:2048
	ds_read_b64_tr_b16 v[220:221], v23 offset:4096
	ds_read_b64_tr_b16 v[222:223], v23 offset:6144
	ds_read_b64_tr_b16 v[224:225], v24 offset:4096
	ds_read_b64_tr_b16 v[226:227], v24 offset:6144
	ds_read_b64_tr_b16 v[228:229], v25 offset:4096
	ds_read_b64_tr_b16 v[230:231], v25 offset:6144
	ds_read_b64_tr_b16 v[232:233], v26 offset:4096
	ds_read_b64_tr_b16 v[234:235], v26 offset:6144
	s_waitcnt lgkmcnt(14)
; #define LAS __attribute__((address_space(3)))
; __device__ __forceinline__ unsigned pk_bf16(float lo, float hi) { const f32x2_t f = {lo, hi}; return __builtin_bit_cast(unsigned, __builtin_convertvector(f, bf16x2_t)); }
; __device__ __forceinline__ void phase_attn(const Params& p, int l, LAS unsigned char* ldsb) {
;     ...
; #pragma unroll
;             for (int kk = 0; kk < 5; ++kk) {
;                 const bf16x8 pa = *(LAS const bf16x8*)(Pw + fr * 168 + kk * 32 + fq * 8);
; #pragma unroll
;                 for (int dt = 0; dt < 4; ++dt) {
;                     const bf16x8 vb = *(LAS const bf16x8*)(Vt + (dt * 16 + fr) * 264 + kstart + kk * 32 + fq * 8);
;                     O[dt] = __builtin_amdgcn_mfma_f32_16x16x32_bf16(pa, vb, O[dt], 0, 0, 0);
;                 }
;             }
; #pragma unroll
;             for (int dt = 0; dt < 4; ++dt)
; #pragma unroll
;                 for (int j = 0; j < 4; ++j) ATT[(size_t)(tokc + q0 + 4 * fq + j) * 512 + hq * 64 + dt * 16 + fr] = (bf16_t)(pk_bf16(O[dt][j], 0.f) & 0xffffu);
;             asm volatile("s_waitcnt lgkmcnt(0)" ::: "memory");
;             __builtin_amdgcn_wave_barrier();
;         }
	v_mfma_f32_16x16x32_bf16 v[160:163], v[196:199], v[140:143], 0
	s_waitcnt lgkmcnt(12)
	v_mfma_f32_16x16x32_bf16 v[164:167], v[200:203], v[140:143], 0
	s_waitcnt lgkmcnt(10)
	v_mfma_f32_16x16x32_bf16 v[168:171], v[204:207], v[140:143], 0
	s_waitcnt lgkmcnt(8)
	v_mfma_f32_16x16x32_bf16 v[172:175], v[208:211], v[140:143], 0
	ds_read_b64_tr_b16 v[196:197], v23 offset:8192
	ds_read_b64_tr_b16 v[198:199], v23 offset:10240
	ds_read_b64_tr_b16 v[200:201], v24 offset:8192
	ds_read_b64_tr_b16 v[202:203], v24 offset:10240
	ds_read_b64_tr_b16 v[204:205], v25 offset:8192
	ds_read_b64_tr_b16 v[206:207], v25 offset:10240
	ds_read_b64_tr_b16 v[208:209], v26 offset:8192
	ds_read_b64_tr_b16 v[210:211], v26 offset:10240
	s_waitcnt lgkmcnt(14)
	v_mfma_f32_16x16x32_bf16 v[160:163], v[220:223], v[144:147], v[160:163]
	s_waitcnt lgkmcnt(12)
	v_mfma_f32_16x16x32_bf16 v[164:167], v[224:227], v[144:147], v[164:167]
	s_waitcnt lgkmcnt(10)
	v_mfma_f32_16x16x32_bf16 v[168:171], v[228:231], v[144:147], v[168:171]
	s_waitcnt lgkmcnt(8)
	v_mfma_f32_16x16x32_bf16 v[172:175], v[232:235], v[144:147], v[172:175]
	ds_read_b64_tr_b16 v[220:221], v23 offset:12288
	ds_read_b64_tr_b16 v[222:223], v23 offset:14336
	ds_read_b64_tr_b16 v[224:225], v24 offset:12288
	ds_read_b64_tr_b16 v[226:227], v24 offset:14336
	ds_read_b64_tr_b16 v[228:229], v25 offset:12288
	ds_read_b64_tr_b16 v[230:231], v25 offset:14336
	ds_read_b64_tr_b16 v[232:233], v26 offset:12288
	ds_read_b64_tr_b16 v[234:235], v26 offset:14336
	s_waitcnt lgkmcnt(14)
	v_mfma_f32_16x16x32_bf16 v[160:163], v[196:199], v[148:151], v[160:163]
	s_waitcnt lgkmcnt(12)
	v_mfma_f32_16x16x32_bf16 v[164:167], v[200:203], v[148:151], v[164:167]
	s_waitcnt lgkmcnt(10)
	v_mfma_f32_16x16x32_bf16 v[168:171], v[204:207], v[148:151], v[168:171]
	s_waitcnt lgkmcnt(8)
	v_mfma_f32_16x16x32_bf16 v[172:175], v[208:211], v[148:151], v[172:175]
	ds_read_b64_tr_b16 v[196:197], v23 offset:16384
	ds_read_b64_tr_b16 v[198:199], v23 offset:18432
	ds_read_b64_tr_b16 v[200:201], v24 offset:16384
	ds_read_b64_tr_b16 v[202:203], v24 offset:18432
	ds_read_b64_tr_b16 v[204:205], v25 offset:16384
	ds_read_b64_tr_b16 v[206:207], v25 offset:18432
	ds_read_b64_tr_b16 v[208:209], v26 offset:16384
	ds_read_b64_tr_b16 v[210:211], v26 offset:18432
	s_waitcnt lgkmcnt(14)
	v_mfma_f32_16x16x32_bf16 v[160:163], v[220:223], v[152:155], v[160:163]
	s_waitcnt lgkmcnt(12)
	v_mfma_f32_16x16x32_bf16 v[164:167], v[224:227], v[152:155], v[164:167]
	s_waitcnt lgkmcnt(10)
	v_mfma_f32_16x16x32_bf16 v[168:171], v[228:231], v[152:155], v[168:171]
	s_waitcnt lgkmcnt(8)
	v_mfma_f32_16x16x32_bf16 v[172:175], v[232:235], v[152:155], v[172:175]
	s_waitcnt lgkmcnt(6)
	v_mfma_f32_16x16x32_bf16 v[160:163], v[196:199], v[156:159], v[160:163]
	s_waitcnt lgkmcnt(4)
	v_mfma_f32_16x16x32_bf16 v[164:167], v[200:203], v[156:159], v[164:167]
	s_waitcnt lgkmcnt(2)
	v_mfma_f32_16x16x32_bf16 v[168:171], v[204:207], v[156:159], v[168:171]
	s_waitcnt lgkmcnt(0)
	v_mfma_f32_16x16x32_bf16 v[172:175], v[208:211], v[156:159], v[172:175]
	s_nop 1
	v_cvt_pk_bf16_f32 v176, v160, v161
	v_cvt_pk_bf16_f32 v177, v162, v163
	global_store_dwordx2 v28, v[176:177], s[42:43] offset:0
	v_cvt_pk_bf16_f32 v176, v164, v165
	v_cvt_pk_bf16_f32 v177, v166, v167
	global_store_dwordx2 v28, v[176:177], s[42:43] offset:32
	v_cvt_pk_bf16_f32 v176, v168, v169
	v_cvt_pk_bf16_f32 v177, v170, v171
	global_store_dwordx2 v28, v[176:177], s[42:43] offset:64
	v_cvt_pk_bf16_f32 v176, v172, v173
	v_cvt_pk_bf16_f32 v177, v174, v175
	global_store_dwordx2 v28, v[176:177], s[42:43] offset:96
	s_waitcnt vmcnt(4)
	s_add_u32 s48, s48, 1
	s_cmp_lt_u32 s48, 8
	s_cbranch_scc1 .Lat_rt
